# grid barrier non-leader path: buffer_inv sc1 issued at arrival (waves parked, polls bypass L1) instead of after release; on top of P9/P10 epilogue rewrite
# speedup vs baseline: 1.0216x; 1.0088x over previous
; __device__ __forceinline__ unsigned xb_ld(unsigned* p)              { return __hip_atomic_load(p, __ATOMIC_RELAXED, __HIP_MEMORY_SCOPE_AGENT); }
; __device__ __forceinline__ unsigned xb_add(unsigned* p, unsigned v) { return __hip_atomic_fetch_add(p, v, __ATOMIC_RELAXED, __HIP_MEMORY_SCOPE_AGENT); }
; #define XB_SPIN(cond, bar) do { unsigned _sp = 0; while (cond) { __builtin_amdgcn_s_sleep(1); \
;     if ((++_sp & 255u) == 0u) { if (xb_ld(&(bar)[XB_TMO])) break; if (_sp > XB_SPIN_CAP) { atomicAdd(&(bar)[XB_TMO], 1u); break; } } } } while (0)
; __device__ __forceinline__ void xcd_barrier(const XcdBarrier& b) {
;     ...
;         const unsigned old = xb_add(&bar[XB_XSUB(b.x)], 1u);
;         const unsigned gen = old / nloc;
;         if (old + 1u == (gen + 1u) * nloc) {
;             __builtin_amdgcn_fence(__ATOMIC_RELEASE, "agent");
;             asm volatile("s_waitcnt vmcnt(0)" ::: "memory");
;             const unsigned og = xb_add(&bar[XB_TOP], 1u);
;             const unsigned tg = og / nx;
;             if (og + 1u == (tg + 1u) * nx) xb_add(&bar[XB_TOPGEN], 1u);
;             else XB_SPIN(xb_ld(&bar[XB_TOPGEN]) == tg, bar);
;             __builtin_amdgcn_fence(__ATOMIC_ACQUIRE, "agent");
;             xb_add(&bar[XB_XGEN(b.x)], 1u);
;             asm volatile("s_waitcnt vmcnt(0)" ::: "memory");
;         } else {
;             XB_SPIN(xb_ld(&bar[XB_XGEN(b.x)]) == gen, bar);
;             __builtin_amdgcn_fence(__ATOMIC_ACQUIRE, "agent");
;             asm volatile("s_waitcnt vmcnt(0)" ::: "memory");
;         }
.LBB0_61:
	s_or_b64 exec, exec, s[34:35]
	v_cvt_f32_u32_e32 v5, v3
	s_waitcnt vmcnt(0)
	v_readfirstlane_b32 s4, v4
	v_sub_u32_e32 v4, 0, v3
	v_rcp_iflag_f32_e32 v5, v5
	v_add_u32_e32 v6, s4, v2
	v_mul_f32_e32 v5, 0x4f7ffffe, v5
	v_cvt_u32_f32_e32 v5, v5
	v_mul_lo_u32 v2, v4, v5
	v_mul_hi_u32 v2, v5, v2
	v_add_u32_e32 v2, v5, v2
	v_mul_hi_u32 v2, v6, v2
	v_mul_lo_u32 v4, v2, v3
	v_sub_u32_e32 v4, v6, v4
	v_add_u32_e32 v5, 1, v2
	v_cmp_ge_u32_e32 vcc, v4, v3
	s_nop 1
	v_cndmask_b32_e32 v2, v2, v5, vcc
	v_sub_u32_e32 v5, v4, v3
	v_cndmask_b32_e32 v4, v4, v5, vcc
	v_add_u32_e32 v5, 1, v2
	v_cmp_ge_u32_e32 vcc, v4, v3
	v_add_u32_e32 v4, 1, v6
	s_nop 0
	v_cndmask_b32_e32 v2, v2, v5, vcc
	v_mul_lo_u32 v5, v3, v2
	v_add_u32_e32 v3, v5, v3
	v_cmp_ne_u32_e32 vcc, v4, v3
	s_and_saveexec_b64 s[4:5], vcc
	s_xor_b64 s[4:5], exec, s[4:5]
	s_cbranch_execz .LBB0_75
	buffer_inv sc1
	s_waitcnt lgkmcnt(0)
	v_mov_b32_e32 v1, 0x2000
	global_load_dword v1, v1, s[2:3] offset:1024 sc1
	s_add_u32 s36, s2, 0x2400
	s_addc_u32 s37, s3, 0
	s_waitcnt vmcnt(0)
	v_cmp_eq_u32_e32 vcc, v1, v2
	s_and_saveexec_b64 s[34:35], vcc
	s_cbranch_execz .LBB0_74
	s_mov_b32 s7, 1
	s_mov_b64 s[38:39], 0
	v_mov_b32_e32 v1, 0
	s_branch .LBB0_65

; __device__ __forceinline__ unsigned xb_ld(unsigned* p)              { return __hip_atomic_load(p, __ATOMIC_RELAXED, __HIP_MEMORY_SCOPE_AGENT); }
; #define XB_SPIN(cond, bar) do { unsigned _sp = 0; while (cond) { __builtin_amdgcn_s_sleep(1); \
;     if ((++_sp & 255u) == 0u) { if (xb_ld(&(bar)[XB_TMO])) break; if (_sp > XB_SPIN_CAP) { atomicAdd(&(bar)[XB_TMO], 1u); break; } } } } while (0)
; __device__ __forceinline__ void xcd_barrier(const XcdBarrier& b) {
;     ...
;             XB_SPIN(xb_ld(&bar[XB_XGEN(b.x)]) == gen, bar);
;             __builtin_amdgcn_fence(__ATOMIC_ACQUIRE, "agent");
;             asm volatile("s_waitcnt vmcnt(0)" ::: "memory");
.LBB0_74:
	s_or_b64 exec, exec, s[34:35]
	s_waitcnt vmcnt(0)
	s_waitcnt vmcnt(0)

; __device__ __forceinline__ unsigned xb_ld(unsigned* p)              { return __hip_atomic_load(p, __ATOMIC_RELAXED, __HIP_MEMORY_SCOPE_AGENT); }
; __device__ __forceinline__ unsigned xb_add(unsigned* p, unsigned v) { return __hip_atomic_fetch_add(p, v, __ATOMIC_RELAXED, __HIP_MEMORY_SCOPE_AGENT); }
; #define XB_SPIN(cond, bar) do { unsigned _sp = 0; while (cond) { __builtin_amdgcn_s_sleep(1); \
;     if ((++_sp & 255u) == 0u) { if (xb_ld(&(bar)[XB_TMO])) break; if (_sp > XB_SPIN_CAP) { atomicAdd(&(bar)[XB_TMO], 1u); break; } } } } while (0)
; __device__ __forceinline__ void xcd_barrier(const XcdBarrier& b) {
;     ...
;         const unsigned old = xb_add(&bar[XB_XSUB(b.x)], 1u);
;         const unsigned gen = old / nloc;
;         if (old + 1u == (gen + 1u) * nloc) {
;             __builtin_amdgcn_fence(__ATOMIC_RELEASE, "agent");
;             asm volatile("s_waitcnt vmcnt(0)" ::: "memory");
;             const unsigned og = xb_add(&bar[XB_TOP], 1u);
;             const unsigned tg = og / nx;
;             if (og + 1u == (tg + 1u) * nx) xb_add(&bar[XB_TOPGEN], 1u);
;             else XB_SPIN(xb_ld(&bar[XB_TOPGEN]) == tg, bar);
;             __builtin_amdgcn_fence(__ATOMIC_ACQUIRE, "agent");
;             xb_add(&bar[XB_XGEN(b.x)], 1u);
;             asm volatile("s_waitcnt vmcnt(0)" ::: "memory");
;         } else {
;             XB_SPIN(xb_ld(&bar[XB_XGEN(b.x)]) == gen, bar);
.LBB0_147:
	s_or_b64 exec, exec, s[4:5]
	v_cvt_f32_u32_e32 v6, v4
	s_waitcnt vmcnt(0)
	v_readfirstlane_b32 s4, v5
	v_sub_u32_e32 v5, 0, v4
	v_rcp_iflag_f32_e32 v6, v6
	v_add_u32_e32 v7, s4, v3
	v_mul_f32_e32 v6, 0x4f7ffffe, v6
	v_cvt_u32_f32_e32 v6, v6
	v_mul_lo_u32 v3, v5, v6
	v_mul_hi_u32 v3, v6, v3
	v_add_u32_e32 v3, v6, v3
	v_mul_hi_u32 v3, v7, v3
	v_mul_lo_u32 v5, v3, v4
	v_sub_u32_e32 v5, v7, v5
	v_add_u32_e32 v6, 1, v3
	v_cmp_ge_u32_e32 vcc, v5, v4
	s_nop 1
	v_cndmask_b32_e32 v3, v3, v6, vcc
	v_sub_u32_e32 v6, v5, v4
	v_cndmask_b32_e32 v5, v5, v6, vcc
	v_add_u32_e32 v6, 1, v3
	v_cmp_ge_u32_e32 vcc, v5, v4
	v_add_u32_e32 v5, 1, v7
	s_nop 0
	v_cndmask_b32_e32 v3, v3, v6, vcc
	v_mul_lo_u32 v6, v4, v3
	v_add_u32_e32 v4, v6, v4
	v_cmp_ne_u32_e32 vcc, v5, v4
	s_and_saveexec_b64 s[4:5], vcc
	s_xor_b64 s[4:5], exec, s[4:5]
	s_cbranch_execz .LBB0_161
	buffer_inv sc1
	s_waitcnt lgkmcnt(0)
	global_load_dword v2, v131, s[72:73] sc1
	s_waitcnt vmcnt(0)
	v_cmp_eq_u32_e32 vcc, v2, v3
	s_and_saveexec_b64 s[6:7], vcc
	s_cbranch_execz .LBB0_160
	s_mov_b64 s[50:51], s[42:43]
	s_mov_b32 s46, 1
	s_mov_b64 s[36:37], 0
	s_branch .LBB0_151

; __device__ __forceinline__ unsigned xb_ld(unsigned* p)              { return __hip_atomic_load(p, __ATOMIC_RELAXED, __HIP_MEMORY_SCOPE_AGENT); }
; #define XB_SPIN(cond, bar) do { unsigned _sp = 0; while (cond) { __builtin_amdgcn_s_sleep(1); \
;     if ((++_sp & 255u) == 0u) { if (xb_ld(&(bar)[XB_TMO])) break; if (_sp > XB_SPIN_CAP) { atomicAdd(&(bar)[XB_TMO], 1u); break; } } } } while (0)
; __device__ __forceinline__ void xcd_barrier(const XcdBarrier& b) {
;     ...
;             XB_SPIN(xb_ld(&bar[XB_XGEN(b.x)]) == gen, bar);
;             __builtin_amdgcn_fence(__ATOMIC_ACQUIRE, "agent");
;             asm volatile("s_waitcnt vmcnt(0)" ::: "memory");
.LBB0_160:
	s_or_b64 exec, exec, s[6:7]
	s_waitcnt vmcnt(0)
	s_waitcnt vmcnt(0)

; __device__ __forceinline__ unsigned xb_ld(unsigned* p)              { return __hip_atomic_load(p, __ATOMIC_RELAXED, __HIP_MEMORY_SCOPE_AGENT); }
; __device__ __forceinline__ unsigned xb_add(unsigned* p, unsigned v) { return __hip_atomic_fetch_add(p, v, __ATOMIC_RELAXED, __HIP_MEMORY_SCOPE_AGENT); }
; #define XB_SPIN(cond, bar) do { unsigned _sp = 0; while (cond) { __builtin_amdgcn_s_sleep(1); \
;     if ((++_sp & 255u) == 0u) { if (xb_ld(&(bar)[XB_TMO])) break; if (_sp > XB_SPIN_CAP) { atomicAdd(&(bar)[XB_TMO], 1u); break; } } } } while (0)
; __device__ __forceinline__ void xcd_barrier(const XcdBarrier& b) {
;     ...
;         const unsigned old = xb_add(&bar[XB_XSUB(b.x)], 1u);
;         const unsigned gen = old / nloc;
;         if (old + 1u == (gen + 1u) * nloc) {
;             __builtin_amdgcn_fence(__ATOMIC_RELEASE, "agent");
;             asm volatile("s_waitcnt vmcnt(0)" ::: "memory");
;             const unsigned og = xb_add(&bar[XB_TOP], 1u);
;             const unsigned tg = og / nx;
;             if (og + 1u == (tg + 1u) * nx) xb_add(&bar[XB_TOPGEN], 1u);
;             else XB_SPIN(xb_ld(&bar[XB_TOPGEN]) == tg, bar);
;             __builtin_amdgcn_fence(__ATOMIC_ACQUIRE, "agent");
;             xb_add(&bar[XB_XGEN(b.x)], 1u);
;             asm volatile("s_waitcnt vmcnt(0)" ::: "memory");
;         } else {
;             XB_SPIN(xb_ld(&bar[XB_XGEN(b.x)]) == gen, bar);
.LBB0_454:
	s_or_b64 exec, exec, s[4:5]
	v_cvt_f32_u32_e32 v6, v4
	s_waitcnt vmcnt(0)
	v_readfirstlane_b32 s4, v5
	v_sub_u32_e32 v5, 0, v4
	v_rcp_iflag_f32_e32 v6, v6
	v_add_u32_e32 v7, s4, v3
	v_mul_f32_e32 v6, 0x4f7ffffe, v6
	v_cvt_u32_f32_e32 v6, v6
	v_mul_lo_u32 v3, v5, v6
	v_mul_hi_u32 v3, v6, v3
	v_add_u32_e32 v3, v6, v3
	v_mul_hi_u32 v3, v7, v3
	v_mul_lo_u32 v5, v3, v4
	v_sub_u32_e32 v5, v7, v5
	v_add_u32_e32 v6, 1, v3
	v_cmp_ge_u32_e32 vcc, v5, v4
	s_nop 1
	v_cndmask_b32_e32 v3, v3, v6, vcc
	v_sub_u32_e32 v6, v5, v4
	v_cndmask_b32_e32 v5, v5, v6, vcc
	v_add_u32_e32 v6, 1, v3
	v_cmp_ge_u32_e32 vcc, v5, v4
	v_add_u32_e32 v5, 1, v7
	s_nop 0
	v_cndmask_b32_e32 v3, v3, v6, vcc
	v_mul_lo_u32 v6, v4, v3
	v_add_u32_e32 v4, v6, v4
	v_cmp_ne_u32_e32 vcc, v5, v4
	s_and_saveexec_b64 s[4:5], vcc
	s_xor_b64 s[4:5], exec, s[4:5]
	s_cbranch_execz .LBB0_468
	buffer_inv sc1
	s_waitcnt lgkmcnt(0)
	global_load_dword v2, v131, s[72:73] sc1
	s_waitcnt vmcnt(0)
	v_cmp_eq_u32_e32 vcc, v2, v3
	s_and_saveexec_b64 s[6:7], vcc
	s_cbranch_execz .LBB0_467
	s_mov_b32 s46, 1
	s_mov_b64 s[36:37], 0
	s_branch .LBB0_458

; __device__ __forceinline__ unsigned xb_ld(unsigned* p)              { return __hip_atomic_load(p, __ATOMIC_RELAXED, __HIP_MEMORY_SCOPE_AGENT); }
; __device__ __forceinline__ unsigned xb_add(unsigned* p, unsigned v) { return __hip_atomic_fetch_add(p, v, __ATOMIC_RELAXED, __HIP_MEMORY_SCOPE_AGENT); }
; #define XB_SPIN(cond, bar) do { unsigned _sp = 0; while (cond) { __builtin_amdgcn_s_sleep(1); \
;     if ((++_sp & 255u) == 0u) { if (xb_ld(&(bar)[XB_TMO])) break; if (_sp > XB_SPIN_CAP) { atomicAdd(&(bar)[XB_TMO], 1u); break; } } } } while (0)
; __device__ __forceinline__ void xcd_barrier(const XcdBarrier& b) {
;     ...
;         const unsigned old = xb_add(&bar[XB_XSUB(b.x)], 1u);
;         const unsigned gen = old / nloc;
;         if (old + 1u == (gen + 1u) * nloc) {
;             __builtin_amdgcn_fence(__ATOMIC_RELEASE, "agent");
;             asm volatile("s_waitcnt vmcnt(0)" ::: "memory");
;             const unsigned og = xb_add(&bar[XB_TOP], 1u);
;             const unsigned tg = og / nx;
;             if (og + 1u == (tg + 1u) * nx) xb_add(&bar[XB_TOPGEN], 1u);
;             else XB_SPIN(xb_ld(&bar[XB_TOPGEN]) == tg, bar);
;             __builtin_amdgcn_fence(__ATOMIC_ACQUIRE, "agent");
;             xb_add(&bar[XB_XGEN(b.x)], 1u);
;             asm volatile("s_waitcnt vmcnt(0)" ::: "memory");
;         } else {
;             XB_SPIN(xb_ld(&bar[XB_XGEN(b.x)]) == gen, bar);
.LBB0_739:
	s_or_b64 exec, exec, s[4:5]
	v_cvt_f32_u32_e32 v6, v4
	s_waitcnt vmcnt(0)
	v_readfirstlane_b32 s4, v5
	v_sub_u32_e32 v5, 0, v4
	v_rcp_iflag_f32_e32 v6, v6
	v_add_u32_e32 v7, s4, v3
	v_mul_f32_e32 v6, 0x4f7ffffe, v6
	v_cvt_u32_f32_e32 v6, v6
	v_mul_lo_u32 v3, v5, v6
	v_mul_hi_u32 v3, v6, v3
	v_add_u32_e32 v3, v6, v3
	v_mul_hi_u32 v3, v7, v3
	v_mul_lo_u32 v5, v3, v4
	v_sub_u32_e32 v5, v7, v5
	v_add_u32_e32 v6, 1, v3
	v_cmp_ge_u32_e32 vcc, v5, v4
	s_nop 1
	v_cndmask_b32_e32 v3, v3, v6, vcc
	v_sub_u32_e32 v6, v5, v4
	v_cndmask_b32_e32 v5, v5, v6, vcc
	v_add_u32_e32 v6, 1, v3
	v_cmp_ge_u32_e32 vcc, v5, v4
	v_add_u32_e32 v5, 1, v7
	s_nop 0
	v_cndmask_b32_e32 v3, v3, v6, vcc
	v_mul_lo_u32 v6, v4, v3
	v_add_u32_e32 v4, v6, v4
	v_cmp_ne_u32_e32 vcc, v5, v4
	s_and_saveexec_b64 s[4:5], vcc
	s_xor_b64 s[4:5], exec, s[4:5]
	s_cbranch_execz .LBB0_753
	buffer_inv sc1
	s_waitcnt lgkmcnt(0)
	global_load_dword v2, v131, s[72:73] sc1
	s_waitcnt vmcnt(0)
	v_cmp_eq_u32_e32 vcc, v2, v3
	s_and_saveexec_b64 s[6:7], vcc
	s_cbranch_execz .LBB0_752
	s_mov_b32 s34, 1
	s_mov_b64 s[36:37], 0
	s_branch .LBB0_743

; __device__ __forceinline__ unsigned xb_ld(unsigned* p)              { return __hip_atomic_load(p, __ATOMIC_RELAXED, __HIP_MEMORY_SCOPE_AGENT); }
; __device__ __forceinline__ unsigned xb_add(unsigned* p, unsigned v) { return __hip_atomic_fetch_add(p, v, __ATOMIC_RELAXED, __HIP_MEMORY_SCOPE_AGENT); }
; #define XB_SPIN(cond, bar) do { unsigned _sp = 0; while (cond) { __builtin_amdgcn_s_sleep(1); \
;     if ((++_sp & 255u) == 0u) { if (xb_ld(&(bar)[XB_TMO])) break; if (_sp > XB_SPIN_CAP) { atomicAdd(&(bar)[XB_TMO], 1u); break; } } } } while (0)
; __device__ __forceinline__ void xcd_barrier(const XcdBarrier& b) {
;     ...
;         const unsigned old = xb_add(&bar[XB_XSUB(b.x)], 1u);
;         const unsigned gen = old / nloc;
;         if (old + 1u == (gen + 1u) * nloc) {
;             __builtin_amdgcn_fence(__ATOMIC_RELEASE, "agent");
;             asm volatile("s_waitcnt vmcnt(0)" ::: "memory");
;             const unsigned og = xb_add(&bar[XB_TOP], 1u);
;             const unsigned tg = og / nx;
;             if (og + 1u == (tg + 1u) * nx) xb_add(&bar[XB_TOPGEN], 1u);
;             else XB_SPIN(xb_ld(&bar[XB_TOPGEN]) == tg, bar);
;             __builtin_amdgcn_fence(__ATOMIC_ACQUIRE, "agent");
;             xb_add(&bar[XB_XGEN(b.x)], 1u);
;             asm volatile("s_waitcnt vmcnt(0)" ::: "memory");
;         } else {
;             XB_SPIN(xb_ld(&bar[XB_XGEN(b.x)]) == gen, bar);
.LBB0_841:
	s_or_b64 exec, exec, s[4:5]
	v_cvt_f32_u32_e32 v6, v4
	s_waitcnt vmcnt(0)
	v_readfirstlane_b32 s4, v5
	v_sub_u32_e32 v5, 0, v4
	v_rcp_iflag_f32_e32 v6, v6
	v_add_u32_e32 v7, s4, v3
	v_mul_f32_e32 v6, 0x4f7ffffe, v6
	v_cvt_u32_f32_e32 v6, v6
	v_mul_lo_u32 v3, v5, v6
	v_mul_hi_u32 v3, v6, v3
	v_add_u32_e32 v3, v6, v3
	v_mul_hi_u32 v3, v7, v3
	v_mul_lo_u32 v5, v3, v4
	v_sub_u32_e32 v5, v7, v5
	v_add_u32_e32 v6, 1, v3
	v_cmp_ge_u32_e32 vcc, v5, v4
	s_nop 1
	v_cndmask_b32_e32 v3, v3, v6, vcc
	v_sub_u32_e32 v6, v5, v4
	v_cndmask_b32_e32 v5, v5, v6, vcc
	v_add_u32_e32 v6, 1, v3
	v_cmp_ge_u32_e32 vcc, v5, v4
	v_add_u32_e32 v5, 1, v7
	s_nop 0
	v_cndmask_b32_e32 v3, v3, v6, vcc
	v_mul_lo_u32 v6, v4, v3
	v_add_u32_e32 v4, v6, v4
	v_cmp_ne_u32_e32 vcc, v5, v4
	s_and_saveexec_b64 s[4:5], vcc
	s_xor_b64 s[4:5], exec, s[4:5]
	s_cbranch_execz .LBB0_855
	buffer_inv sc1
	s_waitcnt lgkmcnt(0)
	v_mov_b32_e32 v2, 0
	global_load_dword v4, v2, s[72:73] sc1
	s_waitcnt vmcnt(0)
	v_cmp_eq_u32_e32 vcc, v4, v3
	s_and_saveexec_b64 s[6:7], vcc
	s_cbranch_execz .LBB0_854
	s_mov_b32 s18, 1
	s_mov_b64 s[8:9], 0
	s_branch .LBB0_845
